# plus: gate values preloaded once, Q fragment loads batched, SGU epilogue U loads hoisted with counted waits
# speedup vs baseline: 1.0013x; 1.0013x over previous
.LBB0_748:
	s_or_b64 exec, exec, s[58:59]
	v_cvt_pk_bf16_f32 v34, v40, v41
	v_cvt_pk_bf16_f32 v35, v36, v38
	v_cvt_pk_bf16_f32 v36, v37, v39
	global_load_dwordx4 v[38:41], v[98:99], off offset:96
	global_load_dwordx4 v[42:45], v[100:101], off offset:96
	v_cvt_pk_bf16_f32 v37, v32, v33
	s_brev_b32 s51, 48
	global_load_dword v32, v[72:73], off
	s_add_i32 s52, s52, s50
	v_add_u32_e32 v86, s76, v86
	v_lshl_add_u64 v[90:91], v[90:91], 0, s[56:57]
	v_lshl_add_u64 v[92:93], v[92:93], 0, s[56:57]
	v_lshl_add_u64 v[94:95], v[94:95], 0, s[56:57]
	v_lshl_add_u64 v[96:97], v[96:97], 0, s[56:57]
	s_cmpk_lt_i32 s52, 0x100
	s_waitcnt vmcnt(2)
	v_mfma_f32_32x32x16_bf16 v[16:31], v[38:41], v[34:37], v[16:31]
	s_waitcnt vmcnt(0)
	s_nop 10
	v_pk_add_f32 v[16:17], v[16:17], v[32:33] op_sel_hi:[1,0]
	v_mfma_f32_32x32x16_bf16 v[0:15], v[42:45], v[34:37], v[0:15]
	v_lshl_add_u64 v[36:37], v[88:89], 0, s[54:55]
	v_add_co_u32_e32 v34, vcc, s51, v36
	v_add_f32_e64 v18, v18, v32
	v_add_f32_e64 v19, v19, v32
	v_addc_co_u32_e32 v35, vcc, 0, v37, vcc
	global_load_dwordx2 v[116:117], v[34:35], off
	global_load_dwordx2 v[118:119], v[34:35], off offset:16
	global_load_dwordx2 v[120:121], v[34:35], off offset:32
	global_load_dwordx2 v[122:123], v[34:35], off offset:48
	global_load_dwordx2 v[124:125], v[34:35], off offset:64
	global_load_dwordx2 v[126:127], v[34:35], off offset:80
	global_load_dwordx2 v[128:129], v[34:35], off offset:96
	global_load_dwordx2 v[130:131], v[34:35], off offset:112
	s_mov_b32 s51, 0x1a000000
	v_pk_add_f32 v[20:21], v[20:21], v[32:33] op_sel_hi:[1,0]
	v_pk_add_f32 v[22:23], v[22:23], v[32:33] op_sel_hi:[1,0]
	s_nop 2
	v_pk_add_f32 v[0:1], v[32:33], v[0:1] op_sel_hi:[0,1]
	v_pk_add_f32 v[2:3], v[32:33], v[2:3] op_sel_hi:[0,1]
	v_pk_add_f32 v[4:5], v[32:33], v[4:5] op_sel_hi:[0,1]
	v_lshl_add_u64 v[88:89], v[88:89], 0, s[56:57]
	s_waitcnt vmcnt(7)
	v_lshlrev_b32_e32 v40, 16, v116
	v_and_b32_e32 v41, 0xffff0000, v116
	v_pk_mul_f32 v[16:17], v[16:17], v[40:41]
	s_nop 0
	v_cvt_pk_bf16_f32 v38, v16, v17
	v_lshlrev_b32_e32 v16, 16, v117
	v_and_b32_e32 v17, 0xffff0000, v117
	v_pk_mul_f32 v[16:17], v[18:19], v[16:17]
	v_cvt_pk_bf16_f32 v39, v16, v17
	v_add_co_u32_e32 v16, vcc, s51, v36
	s_waitcnt vmcnt(6)
	v_lshlrev_b32_e32 v36, 16, v118
	v_addc_co_u32_e32 v17, vcc, 0, v37, vcc
	v_and_b32_e32 v37, 0xffff0000, v118
	v_pk_mul_f32 v[20:21], v[20:21], v[36:37]
	global_store_dwordx2 v[16:17], v[38:39], off
	v_cvt_pk_bf16_f32 v18, v20, v21
	v_lshlrev_b32_e32 v20, 16, v119
	v_and_b32_e32 v21, 0xffff0000, v119
	v_pk_mul_f32 v[20:21], v[22:23], v[20:21]
	v_pk_add_f32 v[22:23], v[24:25], v[32:33] op_sel_hi:[1,0]
	v_cvt_pk_bf16_f32 v19, v20, v21
	global_store_dwordx2 v[16:17], v[18:19], off offset:16
	s_waitcnt vmcnt(7)
	v_lshlrev_b32_e32 v20, 16, v120
	v_and_b32_e32 v21, 0xffff0000, v120
	v_pk_mul_f32 v[20:21], v[22:23], v[20:21]
	v_pk_add_f32 v[22:23], v[26:27], v[32:33] op_sel_hi:[1,0]
	v_cvt_pk_bf16_f32 v18, v20, v21
	v_lshlrev_b32_e32 v20, 16, v121
	v_and_b32_e32 v21, 0xffff0000, v121
	v_pk_mul_f32 v[20:21], v[22:23], v[20:21]
	v_pk_add_f32 v[22:23], v[28:29], v[32:33] op_sel_hi:[1,0]
	v_cvt_pk_bf16_f32 v19, v20, v21
	global_store_dwordx2 v[16:17], v[18:19], off offset:32
	s_waitcnt vmcnt(7)
	v_lshlrev_b32_e32 v20, 16, v122
	v_and_b32_e32 v21, 0xffff0000, v122
	v_pk_mul_f32 v[20:21], v[22:23], v[20:21]
	v_pk_add_f32 v[22:23], v[30:31], v[32:33] op_sel_hi:[1,0]
	v_cvt_pk_bf16_f32 v18, v20, v21
	v_lshlrev_b32_e32 v20, 16, v123
	v_and_b32_e32 v21, 0xffff0000, v123
	v_pk_mul_f32 v[20:21], v[22:23], v[20:21]
	s_nop 0
	v_cvt_pk_bf16_f32 v19, v20, v21
	global_store_dwordx2 v[16:17], v[18:19], off offset:48
	s_waitcnt vmcnt(7)
	v_lshlrev_b32_e32 v20, 16, v124
	v_and_b32_e32 v21, 0xffff0000, v124
	v_lshlrev_b32_e32 v18, 16, v125
	v_and_b32_e32 v19, 0xffff0000, v125
	v_pk_mul_f32 v[0:1], v[0:1], v[20:21]
	v_pk_mul_f32 v[2:3], v[2:3], v[18:19]
	v_cvt_pk_bf16_f32 v0, v0, v1
	v_cvt_pk_bf16_f32 v1, v2, v3
	global_store_dwordx2 v[16:17], v[0:1], off offset:64
	s_waitcnt vmcnt(7)
	v_lshlrev_b32_e32 v2, 16, v126
	v_and_b32_e32 v3, 0xffff0000, v126
	v_pk_mul_f32 v[2:3], v[4:5], v[2:3]
	v_pk_add_f32 v[4:5], v[32:33], v[6:7] op_sel_hi:[0,1]
	v_cvt_pk_bf16_f32 v0, v2, v3
	v_lshlrev_b32_e32 v2, 16, v127
	v_and_b32_e32 v3, 0xffff0000, v127
	v_pk_mul_f32 v[2:3], v[4:5], v[2:3]
	v_pk_add_f32 v[4:5], v[32:33], v[8:9] op_sel_hi:[0,1]
	v_cvt_pk_bf16_f32 v1, v2, v3
	global_store_dwordx2 v[16:17], v[0:1], off offset:80
	s_waitcnt vmcnt(7)
	v_lshlrev_b32_e32 v2, 16, v128
	v_and_b32_e32 v3, 0xffff0000, v128
	v_pk_mul_f32 v[2:3], v[4:5], v[2:3]
	v_pk_add_f32 v[4:5], v[32:33], v[10:11] op_sel_hi:[0,1]
	v_cvt_pk_bf16_f32 v0, v2, v3
	v_lshlrev_b32_e32 v2, 16, v129
	v_and_b32_e32 v3, 0xffff0000, v129
	v_pk_mul_f32 v[2:3], v[4:5], v[2:3]
	v_pk_add_f32 v[4:5], v[32:33], v[12:13] op_sel_hi:[0,1]
	v_cvt_pk_bf16_f32 v1, v2, v3
	global_store_dwordx2 v[16:17], v[0:1], off offset:96
	s_waitcnt vmcnt(7)
	v_lshlrev_b32_e32 v2, 16, v130
	v_and_b32_e32 v3, 0xffff0000, v130
	v_pk_mul_f32 v[2:3], v[4:5], v[2:3]
	v_pk_add_f32 v[4:5], v[32:33], v[14:15] op_sel_hi:[0,1]
	v_cvt_pk_bf16_f32 v0, v2, v3
	v_lshlrev_b32_e32 v2, 16, v131
	v_and_b32_e32 v3, 0xffff0000, v131
	v_pk_mul_f32 v[2:3], v[4:5], v[2:3]
	s_nop 0
	v_cvt_pk_bf16_f32 v1, v2, v3
	global_store_dwordx2 v[16:17], v[0:1], off offset:112
	s_cbranch_scc0 .LBB0_879

.LBB0_783:
	s_or_b64 exec, exec, s[58:59]
	v_cvt_pk_bf16_f32 v34, v41, v36
	v_cvt_pk_bf16_f32 v35, v40, v38
	v_cvt_pk_bf16_f32 v36, v37, v39
	global_load_dwordx4 v[38:41], v[98:99], off offset:-96
	global_load_dwordx4 v[42:45], v[100:101], off offset:-96
	v_cvt_pk_bf16_f32 v37, v32, v33
	v_lshl_add_u64 v[102:103], v[94:95], 0, s[54:55]
	s_brev_b32 s51, 48
	global_load_dword v32, v[76:77], off
	s_waitcnt vmcnt(2)
	v_mfma_f32_32x32x16_bf16 v[16:31], v[38:41], v[34:37], v[16:31]
	s_waitcnt vmcnt(0)
	s_nop 10
	v_pk_add_f32 v[16:17], v[16:17], v[32:33] op_sel_hi:[1,0]
	v_mfma_f32_32x32x16_bf16 v[0:15], v[42:45], v[34:37], v[0:15]
	v_add_co_u32_e32 v34, vcc, s51, v102
	v_add_f32_e64 v18, v18, v32
	v_add_f32_e64 v19, v19, v32
	v_addc_co_u32_e32 v35, vcc, 0, v103, vcc
	global_load_dwordx2 v[116:117], v[34:35], off
	global_load_dwordx2 v[118:119], v[34:35], off offset:16
	global_load_dwordx2 v[120:121], v[34:35], off offset:32
	global_load_dwordx2 v[122:123], v[34:35], off offset:48
	global_load_dwordx2 v[124:125], v[34:35], off offset:64
	global_load_dwordx2 v[126:127], v[34:35], off offset:80
	global_load_dwordx2 v[128:129], v[34:35], off offset:96
	global_load_dwordx2 v[130:131], v[34:35], off offset:112
	s_mov_b32 s51, 0x1a000000
	v_pk_add_f32 v[20:21], v[20:21], v[32:33] op_sel_hi:[1,0]
	v_pk_add_f32 v[22:23], v[22:23], v[32:33] op_sel_hi:[1,0]
	s_nop 3
	v_pk_add_f32 v[0:1], v[32:33], v[0:1] op_sel_hi:[0,1]
	v_pk_add_f32 v[2:3], v[32:33], v[2:3] op_sel_hi:[0,1]
	v_pk_add_f32 v[4:5], v[32:33], v[4:5] op_sel_hi:[0,1]
	s_waitcnt vmcnt(7)
	v_lshlrev_b32_e32 v38, 16, v116
	v_and_b32_e32 v39, 0xffff0000, v116
	v_pk_mul_f32 v[16:17], v[16:17], v[38:39]
	s_nop 0
	v_cvt_pk_bf16_f32 v36, v16, v17
	v_lshlrev_b32_e32 v16, 16, v117
	v_and_b32_e32 v17, 0xffff0000, v117
	v_pk_mul_f32 v[16:17], v[18:19], v[16:17]
	v_cvt_pk_bf16_f32 v37, v16, v17
	v_add_co_u32_e32 v16, vcc, s51, v102
	s_nop 1
	v_addc_co_u32_e32 v17, vcc, 0, v103, vcc
	global_store_dwordx2 v[16:17], v[36:37], off
	s_waitcnt vmcnt(7)
	v_lshlrev_b32_e32 v36, 16, v118
	v_and_b32_e32 v37, 0xffff0000, v118
	v_pk_mul_f32 v[20:21], v[20:21], v[36:37]
	s_nop 0
	v_cvt_pk_bf16_f32 v18, v20, v21
	v_lshlrev_b32_e32 v20, 16, v119
	v_and_b32_e32 v21, 0xffff0000, v119
	v_pk_mul_f32 v[20:21], v[22:23], v[20:21]
	v_pk_add_f32 v[22:23], v[24:25], v[32:33] op_sel_hi:[1,0]
	v_cvt_pk_bf16_f32 v19, v20, v21
	global_store_dwordx2 v[16:17], v[18:19], off offset:16
	s_waitcnt vmcnt(7)
	v_lshlrev_b32_e32 v20, 16, v120
	v_and_b32_e32 v21, 0xffff0000, v120
	v_pk_mul_f32 v[20:21], v[22:23], v[20:21]
	v_pk_add_f32 v[22:23], v[26:27], v[32:33] op_sel_hi:[1,0]
	v_cvt_pk_bf16_f32 v18, v20, v21
	v_lshlrev_b32_e32 v20, 16, v121
	v_and_b32_e32 v21, 0xffff0000, v121
	v_pk_mul_f32 v[20:21], v[22:23], v[20:21]
	v_pk_add_f32 v[22:23], v[28:29], v[32:33] op_sel_hi:[1,0]
	v_cvt_pk_bf16_f32 v19, v20, v21
	global_store_dwordx2 v[16:17], v[18:19], off offset:32
	s_waitcnt vmcnt(7)
	v_lshlrev_b32_e32 v20, 16, v122
	v_and_b32_e32 v21, 0xffff0000, v122
	v_pk_mul_f32 v[20:21], v[22:23], v[20:21]
	v_pk_add_f32 v[22:23], v[30:31], v[32:33] op_sel_hi:[1,0]
	v_cvt_pk_bf16_f32 v18, v20, v21
	v_lshlrev_b32_e32 v20, 16, v123
	v_and_b32_e32 v21, 0xffff0000, v123
	v_pk_mul_f32 v[20:21], v[22:23], v[20:21]
	s_nop 0
	v_cvt_pk_bf16_f32 v19, v20, v21
	global_store_dwordx2 v[16:17], v[18:19], off offset:48
	s_waitcnt vmcnt(7)
	v_lshlrev_b32_e32 v20, 16, v124
	v_and_b32_e32 v21, 0xffff0000, v124
	v_lshlrev_b32_e32 v18, 16, v125
	v_and_b32_e32 v19, 0xffff0000, v125
	v_pk_mul_f32 v[0:1], v[0:1], v[20:21]
	v_pk_mul_f32 v[2:3], v[2:3], v[18:19]
	v_cvt_pk_bf16_f32 v0, v0, v1
	v_cvt_pk_bf16_f32 v1, v2, v3
	global_store_dwordx2 v[16:17], v[0:1], off offset:64
	s_waitcnt vmcnt(7)
	v_lshlrev_b32_e32 v2, 16, v126
	v_and_b32_e32 v3, 0xffff0000, v126
	v_pk_mul_f32 v[2:3], v[4:5], v[2:3]
	v_pk_add_f32 v[4:5], v[32:33], v[6:7] op_sel_hi:[0,1]
	v_cvt_pk_bf16_f32 v0, v2, v3
	v_lshlrev_b32_e32 v2, 16, v127
	v_and_b32_e32 v3, 0xffff0000, v127
	v_pk_mul_f32 v[2:3], v[4:5], v[2:3]
	v_pk_add_f32 v[4:5], v[32:33], v[8:9] op_sel_hi:[0,1]
	v_cvt_pk_bf16_f32 v1, v2, v3
	global_store_dwordx2 v[16:17], v[0:1], off offset:80
	s_waitcnt vmcnt(7)
	v_lshlrev_b32_e32 v2, 16, v128
	v_and_b32_e32 v3, 0xffff0000, v128
	v_pk_mul_f32 v[2:3], v[4:5], v[2:3]
	v_pk_add_f32 v[4:5], v[32:33], v[10:11] op_sel_hi:[0,1]
	v_cvt_pk_bf16_f32 v0, v2, v3
	v_lshlrev_b32_e32 v2, 16, v129
	v_and_b32_e32 v3, 0xffff0000, v129
	v_pk_mul_f32 v[2:3], v[4:5], v[2:3]
	v_pk_add_f32 v[4:5], v[32:33], v[12:13] op_sel_hi:[0,1]
	v_cvt_pk_bf16_f32 v1, v2, v3
	global_store_dwordx2 v[16:17], v[0:1], off offset:96
	s_waitcnt vmcnt(7)
	v_lshlrev_b32_e32 v2, 16, v130
	v_and_b32_e32 v3, 0xffff0000, v130
	v_pk_mul_f32 v[2:3], v[4:5], v[2:3]
	v_pk_add_f32 v[4:5], v[32:33], v[14:15] op_sel_hi:[0,1]
	v_cvt_pk_bf16_f32 v0, v2, v3
	v_lshlrev_b32_e32 v2, 16, v131
	v_and_b32_e32 v3, 0xffff0000, v131
	v_pk_mul_f32 v[2:3], v[4:5], v[2:3]
	s_nop 0
	v_cvt_pk_bf16_f32 v1, v2, v3
	global_store_dwordx2 v[16:17], v[0:1], off offset:112
	global_load_dwordx4 v[0:3], v[78:79], off offset:16
	s_nop 0
	global_load_dwordx4 v[4:7], v[78:79], off
	ds_read_b128 v[36:39], v105
	ds_read_b128 v[32:35], v105 offset:16
	s_waitcnt vmcnt(1) lgkmcnt(0)
	v_pk_mul_f32 v[8:9], v[0:1], v[32:33]
	s_waitcnt vmcnt(0)
	v_pk_mul_f32 v[4:5], v[4:5], v[36:37]
	v_pk_mul_f32 v[6:7], v[6:7], v[38:39]
	v_pk_mul_f32 v[10:11], v[2:3], v[34:35]
	v_cvt_pk_bf16_f32 v0, v4, v5
	v_cvt_pk_bf16_f32 v1, v6, v7
	v_cvt_pk_bf16_f32 v2, v8, v9
	v_cvt_pk_bf16_f32 v3, v10, v11
	global_load_dwordx4 v[4:7], v[98:99], off offset:-128
	global_load_dwordx4 v[8:11], v[100:101], off offset:-128
	global_load_dwordx4 v[48:51], v[78:79], off offset:80
	global_load_dwordx4 v[44:47], v[78:79], off offset:64
	ds_read_b128 v[40:43], v105 offset:64
	s_waitcnt vmcnt(3)
	v_mfma_f32_32x32x16_bf16 v[16:31], v[4:7], v[0:3], 0
	s_waitcnt vmcnt(0) lgkmcnt(0)
	v_mul_f32_e64 v52, v44, v40
	v_mul_f32_e64 v53, v45, v41
	v_mul_f32_e64 v54, v46, v42
	v_mul_f32_e64 v55, v47, v43
	ds_read_b128 v[44:47], v105 offset:80
	s_waitcnt lgkmcnt(0)
	v_pk_mul_f32 v[58:59], v[48:49], v[44:45]
	v_pk_mul_f32 v[60:61], v[50:51], v[46:47]
	v_cvt_pk_bf16_f32 v48, v52, v53
	v_cvt_pk_bf16_f32 v49, v54, v55
	v_cvt_pk_bf16_f32 v50, v58, v59
	v_cvt_pk_bf16_f32 v51, v60, v61
	global_load_dwordx4 v[52:55], v[98:99], off offset:-96
	global_load_dwordx4 v[58:61], v[100:101], off offset:-96
	v_mfma_f32_32x32x16_bf16 v[0:15], v[8:11], v[0:3], 0
	s_waitcnt vmcnt(1)
	v_mfma_f32_32x32x16_bf16 v[16:31], v[52:55], v[48:51], v[16:31]
	s_waitcnt vmcnt(0)
	v_mfma_f32_32x32x16_bf16 v[0:15], v[58:61], v[48:51], v[0:15]
	global_load_dwordx4 v[48:51], v[78:79], off offset:144
	global_load_dwordx4 v[52:55], v[78:79], off offset:128
	s_mov_b64 s[58:59], exec
	v_readlane_b32 s80, v254, 49
	v_readlane_b32 s81, v254, 50
	s_and_b64 s[80:81], s[58:59], s[80:81]
	s_mov_b64 exec, s[80:81]
	s_cbranch_execz .LBB0_785
	ds_read_b32 v56, v105 offset:128
	s_waitcnt vmcnt(0) lgkmcnt(0)
	v_mul_f32_e32 v56, v52, v56

.LBB0_815:
	s_or_b64 exec, exec, s[58:59]
	v_cvt_pk_bf16_f32 v50, v57, v56
	v_cvt_pk_bf16_f32 v51, v52, v54
	v_cvt_pk_bf16_f32 v52, v53, v55
	global_load_dwordx4 v[54:57], v[98:99], off offset:-32
	global_load_dwordx4 v[58:61], v[100:101], off offset:-32
	v_cvt_pk_bf16_f32 v53, v48, v49
	s_brev_b32 s51, 48
	global_load_dword v48, v[80:81], off
	s_waitcnt vmcnt(2)
	v_mfma_f32_32x32x16_bf16 v[16:31], v[54:57], v[50:53], v[16:31]
	s_waitcnt vmcnt(0)
	s_nop 10
	v_pk_add_f32 v[16:17], v[16:17], v[48:49] op_sel_hi:[1,0]
	v_mfma_f32_32x32x16_bf16 v[0:15], v[58:61], v[50:53], v[0:15]
	v_lshl_add_u64 v[52:53], v[96:97], 0, s[54:55]
	v_add_co_u32_e32 v50, vcc, s51, v52
	v_add_f32_e64 v18, v18, v48
	v_add_f32_e64 v19, v19, v48
	v_addc_co_u32_e32 v51, vcc, 0, v53, vcc
	global_load_dwordx2 v[116:117], v[50:51], off
	global_load_dwordx2 v[118:119], v[50:51], off offset:16
	global_load_dwordx2 v[120:121], v[50:51], off offset:32
	global_load_dwordx2 v[122:123], v[50:51], off offset:48
	global_load_dwordx2 v[124:125], v[50:51], off offset:64
	global_load_dwordx2 v[126:127], v[50:51], off offset:80
	global_load_dwordx2 v[128:129], v[50:51], off offset:96
	global_load_dwordx2 v[130:131], v[50:51], off offset:112
	s_mov_b32 s51, 0x1a000000
	v_pk_add_f32 v[20:21], v[20:21], v[48:49] op_sel_hi:[1,0]
	v_pk_add_f32 v[22:23], v[22:23], v[48:49] op_sel_hi:[1,0]
	s_nop 2
	v_pk_add_f32 v[0:1], v[48:49], v[0:1] op_sel_hi:[0,1]
	v_pk_add_f32 v[2:3], v[48:49], v[2:3] op_sel_hi:[0,1]
	v_pk_add_f32 v[4:5], v[48:49], v[4:5] op_sel_hi:[0,1]
	s_waitcnt vmcnt(7)
	v_lshlrev_b32_e32 v56, 16, v116
	v_and_b32_e32 v57, 0xffff0000, v116
	v_pk_mul_f32 v[16:17], v[16:17], v[56:57]
	s_nop 0
	v_cvt_pk_bf16_f32 v54, v16, v17
	v_lshlrev_b32_e32 v16, 16, v117
	v_and_b32_e32 v17, 0xffff0000, v117
	v_pk_mul_f32 v[16:17], v[18:19], v[16:17]
	v_cvt_pk_bf16_f32 v55, v16, v17
	v_add_co_u32_e32 v16, vcc, s51, v52
	s_waitcnt vmcnt(6)
	v_lshlrev_b32_e32 v52, 16, v118
	v_addc_co_u32_e32 v17, vcc, 0, v53, vcc
	v_and_b32_e32 v53, 0xffff0000, v118
	v_pk_mul_f32 v[20:21], v[20:21], v[52:53]
	global_store_dwordx2 v[16:17], v[54:55], off
	v_cvt_pk_bf16_f32 v18, v20, v21
	v_lshlrev_b32_e32 v20, 16, v119
	v_and_b32_e32 v21, 0xffff0000, v119
	v_pk_mul_f32 v[20:21], v[22:23], v[20:21]
	v_pk_add_f32 v[22:23], v[24:25], v[48:49] op_sel_hi:[1,0]
	v_cvt_pk_bf16_f32 v19, v20, v21
	global_store_dwordx2 v[16:17], v[18:19], off offset:16
	s_waitcnt vmcnt(7)
	v_lshlrev_b32_e32 v20, 16, v120
	v_and_b32_e32 v21, 0xffff0000, v120
	v_pk_mul_f32 v[20:21], v[22:23], v[20:21]
	v_pk_add_f32 v[22:23], v[26:27], v[48:49] op_sel_hi:[1,0]
	v_cvt_pk_bf16_f32 v18, v20, v21
	v_lshlrev_b32_e32 v20, 16, v121
	v_and_b32_e32 v21, 0xffff0000, v121
	v_pk_mul_f32 v[20:21], v[22:23], v[20:21]
	v_pk_add_f32 v[22:23], v[28:29], v[48:49] op_sel_hi:[1,0]
	v_cvt_pk_bf16_f32 v19, v20, v21
	global_store_dwordx2 v[16:17], v[18:19], off offset:32
	s_waitcnt vmcnt(7)
	v_lshlrev_b32_e32 v20, 16, v122
	v_and_b32_e32 v21, 0xffff0000, v122
	v_pk_mul_f32 v[20:21], v[22:23], v[20:21]
	v_pk_add_f32 v[22:23], v[30:31], v[48:49] op_sel_hi:[1,0]
	v_cvt_pk_bf16_f32 v18, v20, v21
	v_lshlrev_b32_e32 v20, 16, v123
	v_and_b32_e32 v21, 0xffff0000, v123
	v_pk_mul_f32 v[20:21], v[22:23], v[20:21]
	s_nop 0
	v_cvt_pk_bf16_f32 v19, v20, v21
	global_store_dwordx2 v[16:17], v[18:19], off offset:48
	s_waitcnt vmcnt(7)
	v_lshlrev_b32_e32 v20, 16, v124
	v_and_b32_e32 v21, 0xffff0000, v124
	v_lshlrev_b32_e32 v18, 16, v125
	v_and_b32_e32 v19, 0xffff0000, v125
	v_pk_mul_f32 v[0:1], v[0:1], v[20:21]
	v_pk_mul_f32 v[2:3], v[2:3], v[18:19]
	v_cvt_pk_bf16_f32 v0, v0, v1
	v_cvt_pk_bf16_f32 v1, v2, v3
	global_store_dwordx2 v[16:17], v[0:1], off offset:64
	s_waitcnt vmcnt(7)
	v_lshlrev_b32_e32 v2, 16, v126
	v_and_b32_e32 v3, 0xffff0000, v126
	v_pk_mul_f32 v[2:3], v[4:5], v[2:3]
	v_pk_add_f32 v[4:5], v[48:49], v[6:7] op_sel_hi:[0,1]
	v_cvt_pk_bf16_f32 v0, v2, v3
	v_lshlrev_b32_e32 v2, 16, v127
	v_and_b32_e32 v3, 0xffff0000, v127
	v_pk_mul_f32 v[2:3], v[4:5], v[2:3]
	v_pk_add_f32 v[4:5], v[48:49], v[8:9] op_sel_hi:[0,1]
	v_cvt_pk_bf16_f32 v1, v2, v3
	global_store_dwordx2 v[16:17], v[0:1], off offset:80
	s_waitcnt vmcnt(7)
	v_lshlrev_b32_e32 v2, 16, v128
	v_and_b32_e32 v3, 0xffff0000, v128
	v_pk_mul_f32 v[2:3], v[4:5], v[2:3]
	v_pk_add_f32 v[4:5], v[48:49], v[10:11] op_sel_hi:[0,1]
	v_cvt_pk_bf16_f32 v0, v2, v3
	v_lshlrev_b32_e32 v2, 16, v129
	v_and_b32_e32 v3, 0xffff0000, v129
	v_pk_mul_f32 v[2:3], v[4:5], v[2:3]
	v_pk_add_f32 v[4:5], v[48:49], v[12:13] op_sel_hi:[0,1]
	v_cvt_pk_bf16_f32 v1, v2, v3
	global_store_dwordx2 v[16:17], v[0:1], off offset:96
	s_waitcnt vmcnt(7)
	v_lshlrev_b32_e32 v2, 16, v130
	v_and_b32_e32 v3, 0xffff0000, v130
	v_pk_mul_f32 v[2:3], v[4:5], v[2:3]
	v_pk_add_f32 v[4:5], v[48:49], v[14:15] op_sel_hi:[0,1]
	v_cvt_pk_bf16_f32 v0, v2, v3
	v_lshlrev_b32_e32 v2, 16, v131
	v_and_b32_e32 v3, 0xffff0000, v131
	v_pk_mul_f32 v[2:3], v[4:5], v[2:3]
	s_nop 0
	v_cvt_pk_bf16_f32 v1, v2, v3
	global_store_dwordx2 v[16:17], v[0:1], off offset:112
	global_load_dwordx4 v[0:3], v[82:83], off offset:16
	s_nop 0
	global_load_dwordx4 v[4:7], v[82:83], off
	s_waitcnt vmcnt(1)
	v_pk_mul_f32 v[8:9], v[32:33], v[0:1]
	s_waitcnt vmcnt(0)
	v_pk_mul_f32 v[4:5], v[36:37], v[4:5]
	v_pk_mul_f32 v[6:7], v[38:39], v[6:7]
	v_pk_mul_f32 v[10:11], v[34:35], v[2:3]
	v_cvt_pk_bf16_f32 v0, v4, v5
	v_cvt_pk_bf16_f32 v1, v6, v7
	v_cvt_pk_bf16_f32 v2, v8, v9
	v_cvt_pk_bf16_f32 v3, v10, v11
	global_load_dwordx4 v[4:7], v[98:99], off offset:-128
	global_load_dwordx4 v[8:11], v[100:101], off offset:-128
	global_load_dwordx4 v[48:51], v[82:83], off offset:80
	global_load_dwordx4 v[52:55], v[82:83], off offset:64
	s_waitcnt vmcnt(3)
	v_mfma_f32_32x32x16_bf16 v[16:31], v[4:7], v[0:3], 0
	s_waitcnt vmcnt(1)
	v_mul_f32_e64 v56, v44, v48
	v_mul_f32_e64 v57, v45, v49
	s_waitcnt vmcnt(0)
	v_mul_f32_e64 v52, v40, v52
	v_mul_f32_e64 v53, v41, v53
	v_pk_mul_f32 v[54:55], v[42:43], v[54:55]
	v_pk_mul_f32 v[58:59], v[46:47], v[50:51]
	v_cvt_pk_bf16_f32 v48, v52, v53
	v_cvt_pk_bf16_f32 v49, v54, v55
	v_cvt_pk_bf16_f32 v50, v56, v57
	v_cvt_pk_bf16_f32 v51, v58, v59
	global_load_dwordx4 v[52:55], v[98:99], off offset:-96
	global_load_dwordx4 v[56:59], v[100:101], off offset:-96
	v_mfma_f32_32x32x16_bf16 v[0:15], v[8:11], v[0:3], 0
	s_waitcnt vmcnt(0)
	v_mfma_f32_32x32x16_bf16 v[0:15], v[56:59], v[48:51], v[0:15]
	global_load_dwordx4 v[56:59], v[82:83], off offset:144
	global_load_dwordx4 v[60:63], v[82:83], off offset:128
	v_mfma_f32_32x32x16_bf16 v[16:31], v[52:55], v[48:51], v[16:31]
	ds_read_b128 v[52:55], v105 offset:128
	ds_read_b128 v[48:51], v105 offset:144
	s_waitcnt vmcnt(1) lgkmcnt(0)
	v_mul_f32_e64 v64, v56, v48
	v_mul_f32_e64 v65, v57, v49
	s_waitcnt vmcnt(0)
	v_pk_mul_f32 v[60:61], v[60:61], v[52:53]
	v_pk_mul_f32 v[62:63], v[62:63], v[54:55]
	v_pk_mul_f32 v[66:67], v[58:59], v[50:51]
	v_cvt_pk_bf16_f32 v56, v60, v61
	v_cvt_pk_bf16_f32 v57, v62, v63
	v_cvt_pk_bf16_f32 v58, v64, v65
	v_cvt_pk_bf16_f32 v59, v66, v67
	global_load_dwordx4 v[60:63], v[98:99], off offset:-64
	global_load_dwordx4 v[64:67], v[100:101], off offset:-64
	s_waitcnt vmcnt(1)
	v_mfma_f32_32x32x16_bf16 v[16:31], v[60:63], v[56:59], v[16:31]
	s_waitcnt vmcnt(0)
	v_mfma_f32_32x32x16_bf16 v[0:15], v[64:67], v[56:59], v[0:15]
	global_load_dwordx4 v[64:67], v[82:83], off offset:208
	global_load_dwordx4 v[60:63], v[82:83], off offset:192
	ds_read_b128 v[56:59], v105 offset:192
	s_waitcnt vmcnt(0) lgkmcnt(0)
	v_mul_f32_e64 v68, v60, v56
	v_mul_f32_e64 v69, v61, v57
	v_pk_mul_f32 v[70:71], v[62:63], v[58:59]
	ds_read_b128 v[60:63], v105 offset:208
	s_waitcnt lgkmcnt(0)
	v_pk_mul_f32 v[106:107], v[64:65], v[60:61]
	v_pk_mul_f32 v[108:109], v[66:67], v[62:63]
	v_cvt_pk_bf16_f32 v64, v68, v69
	v_cvt_pk_bf16_f32 v65, v70, v71
	v_cvt_pk_bf16_f32 v66, v106, v107
	v_cvt_pk_bf16_f32 v67, v108, v109
	global_load_dwordx4 v[68:71], v[98:99], off offset:-32
	global_load_dwordx4 v[106:109], v[100:101], off offset:-32
	s_waitcnt vmcnt(1)
	v_mfma_f32_32x32x16_bf16 v[16:31], v[68:71], v[64:67], v[16:31]
	s_waitcnt vmcnt(0)
	v_mfma_f32_32x32x16_bf16 v[0:15], v[106:109], v[64:67], v[0:15]
	global_load_dwordx4 v[64:67], v[82:83], off offset:272
	global_load_dwordx4 v[68:71], v[82:83], off offset:256
	s_and_saveexec_b64 s[58:59], s[8:9]
	s_cbranch_execz .LBB0_817
	ds_read_b32 v87, v105 offset:256
	s_waitcnt vmcnt(0) lgkmcnt(0)
	v_mul_f32_e32 v87, v68, v87

.LBB0_847:
	s_or_b64 exec, exec, s[58:59]
	v_cvt_pk_bf16_f32 v107, v68, v70
	v_cvt_pk_bf16_f32 v108, v69, v71
	v_cvt_pk_bf16_f32 v109, v64, v66
	global_load_dwordx4 v[66:69], v[98:99], off offset:32
	global_load_dwordx4 v[110:113], v[100:101], off offset:32
	v_cvt_pk_bf16_f32 v106, v106, v87
	s_mov_b32 s51, 0xc010000
	global_load_dword v64, v[76:77], off offset:256
	s_waitcnt vmcnt(2)
	v_mfma_f32_32x32x16_bf16 v[16:31], v[66:69], v[106:109], v[16:31]
	v_add_co_u32_e32 v66, vcc, s51, v102
	s_mov_b32 s51, 0x1a010000
	s_nop 0
	v_addc_co_u32_e32 v67, vcc, 0, v103, vcc
	global_load_dwordx2 v[116:117], v[66:67], off
	global_load_dwordx2 v[118:119], v[66:67], off offset:16
	global_load_dwordx2 v[120:121], v[66:67], off offset:32
	global_load_dwordx2 v[122:123], v[66:67], off offset:48
	global_load_dwordx2 v[124:125], v[66:67], off offset:64
	global_load_dwordx2 v[126:127], v[66:67], off offset:80
	global_load_dwordx2 v[128:129], v[66:67], off offset:96
	global_load_dwordx2 v[130:131], v[66:67], off offset:112
	s_waitcnt vmcnt(1)
	s_nop 5
	v_pk_add_f32 v[16:17], v[16:17], v[64:65] op_sel_hi:[1,0]
	v_pk_add_f32 v[18:19], v[18:19], v[64:65] op_sel_hi:[1,0]
	v_pk_add_f32 v[20:21], v[20:21], v[64:65] op_sel_hi:[1,0]
	v_pk_add_f32 v[22:23], v[22:23], v[64:65] op_sel_hi:[1,0]
	v_mfma_f32_32x32x16_bf16 v[0:15], v[110:113], v[106:109], v[0:15]
	s_waitcnt vmcnt(7)
	v_lshlrev_b32_e32 v70, 16, v116
	v_and_b32_e32 v71, 0xffff0000, v116
	v_mul_f32_e64 v16, v16, v70
	v_mul_f32_e64 v17, v17, v71
	s_nop 6
	v_pk_add_f32 v[0:1], v[64:65], v[0:1] op_sel_hi:[0,1]
	v_cvt_pk_bf16_f32 v68, v16, v17
	v_lshlrev_b32_e32 v16, 16, v117
	v_and_b32_e32 v17, 0xffff0000, v117
	v_pk_mul_f32 v[16:17], v[18:19], v[16:17]
	v_cvt_pk_bf16_f32 v69, v16, v17
	v_add_co_u32_e32 v16, vcc, s51, v102
	v_pk_add_f32 v[2:3], v[64:65], v[2:3] op_sel_hi:[0,1]
	s_nop 0
	v_addc_co_u32_e32 v17, vcc, 0, v103, vcc
	global_store_dwordx2 v[16:17], v[68:69], off
	v_pk_add_f32 v[4:5], v[64:65], v[4:5] op_sel_hi:[0,1]
	s_waitcnt vmcnt(7)
	v_lshlrev_b32_e32 v68, 16, v118
	v_and_b32_e32 v69, 0xffff0000, v118
	v_pk_mul_f32 v[20:21], v[20:21], v[68:69]
	s_nop 0
	v_cvt_pk_bf16_f32 v18, v20, v21
	v_lshlrev_b32_e32 v20, 16, v119
	v_and_b32_e32 v21, 0xffff0000, v119
	v_pk_mul_f32 v[20:21], v[22:23], v[20:21]
	v_pk_add_f32 v[22:23], v[24:25], v[64:65] op_sel_hi:[1,0]
	v_cvt_pk_bf16_f32 v19, v20, v21
	global_store_dwordx2 v[16:17], v[18:19], off offset:16
	s_waitcnt vmcnt(7)
	v_lshlrev_b32_e32 v20, 16, v120
	v_and_b32_e32 v21, 0xffff0000, v120
	v_pk_mul_f32 v[20:21], v[22:23], v[20:21]
	v_pk_add_f32 v[22:23], v[26:27], v[64:65] op_sel_hi:[1,0]
	v_cvt_pk_bf16_f32 v18, v20, v21
	v_lshlrev_b32_e32 v20, 16, v121
	v_and_b32_e32 v21, 0xffff0000, v121
	v_pk_mul_f32 v[20:21], v[22:23], v[20:21]
	v_pk_add_f32 v[22:23], v[28:29], v[64:65] op_sel_hi:[1,0]
	v_cvt_pk_bf16_f32 v19, v20, v21
	global_store_dwordx2 v[16:17], v[18:19], off offset:32
	s_waitcnt vmcnt(7)
	v_lshlrev_b32_e32 v20, 16, v122
	v_and_b32_e32 v21, 0xffff0000, v122
	v_pk_mul_f32 v[20:21], v[22:23], v[20:21]
	v_pk_add_f32 v[22:23], v[30:31], v[64:65] op_sel_hi:[1,0]
	v_cvt_pk_bf16_f32 v18, v20, v21
	v_lshlrev_b32_e32 v20, 16, v123
	v_and_b32_e32 v21, 0xffff0000, v123
	v_pk_mul_f32 v[20:21], v[22:23], v[20:21]
	s_nop 0
	v_cvt_pk_bf16_f32 v19, v20, v21
	global_store_dwordx2 v[16:17], v[18:19], off offset:48
	s_waitcnt vmcnt(7)
	v_lshlrev_b32_e32 v20, 16, v124
	v_and_b32_e32 v21, 0xffff0000, v124
	v_lshlrev_b32_e32 v18, 16, v125
	v_and_b32_e32 v19, 0xffff0000, v125
	v_pk_mul_f32 v[0:1], v[0:1], v[20:21]
	v_pk_mul_f32 v[2:3], v[2:3], v[18:19]
	v_cvt_pk_bf16_f32 v0, v0, v1
	v_cvt_pk_bf16_f32 v1, v2, v3
	global_store_dwordx2 v[16:17], v[0:1], off offset:64
	s_waitcnt vmcnt(7)
	v_lshlrev_b32_e32 v2, 16, v126
	v_and_b32_e32 v3, 0xffff0000, v126
	v_pk_mul_f32 v[2:3], v[4:5], v[2:3]
	v_pk_add_f32 v[4:5], v[64:65], v[6:7] op_sel_hi:[0,1]
	v_cvt_pk_bf16_f32 v0, v2, v3
	v_lshlrev_b32_e32 v2, 16, v127
	v_and_b32_e32 v3, 0xffff0000, v127
	v_pk_mul_f32 v[2:3], v[4:5], v[2:3]
	v_pk_add_f32 v[4:5], v[64:65], v[8:9] op_sel_hi:[0,1]
	v_cvt_pk_bf16_f32 v1, v2, v3
	global_store_dwordx2 v[16:17], v[0:1], off offset:80
	s_waitcnt vmcnt(7)
	v_lshlrev_b32_e32 v2, 16, v128
	v_and_b32_e32 v3, 0xffff0000, v128
	v_pk_mul_f32 v[2:3], v[4:5], v[2:3]
	v_pk_add_f32 v[4:5], v[64:65], v[10:11] op_sel_hi:[0,1]
	v_cvt_pk_bf16_f32 v0, v2, v3
	v_lshlrev_b32_e32 v2, 16, v129
	v_and_b32_e32 v3, 0xffff0000, v129
	v_pk_mul_f32 v[2:3], v[4:5], v[2:3]
	v_pk_add_f32 v[4:5], v[64:65], v[12:13] op_sel_hi:[0,1]
	v_cvt_pk_bf16_f32 v1, v2, v3
	global_store_dwordx2 v[16:17], v[0:1], off offset:96
	s_waitcnt vmcnt(7)
	v_lshlrev_b32_e32 v2, 16, v130
	v_and_b32_e32 v3, 0xffff0000, v130
	v_pk_mul_f32 v[2:3], v[4:5], v[2:3]
	v_pk_add_f32 v[4:5], v[64:65], v[14:15] op_sel_hi:[0,1]
	v_cvt_pk_bf16_f32 v0, v2, v3
	v_lshlrev_b32_e32 v2, 16, v131
	v_and_b32_e32 v3, 0xffff0000, v131
	v_pk_mul_f32 v[2:3], v[4:5], v[2:3]
	s_nop 0
	v_cvt_pk_bf16_f32 v1, v2, v3
	global_store_dwordx2 v[16:17], v[0:1], off offset:112
	global_load_dwordx4 v[0:3], v[84:85], off offset:16
	s_nop 0
	global_load_dwordx4 v[4:7], v[84:85], off
	s_waitcnt vmcnt(1)
	v_pk_mul_f32 v[8:9], v[32:33], v[0:1]
	s_waitcnt vmcnt(0)
	v_pk_mul_f32 v[4:5], v[36:37], v[4:5]
	v_pk_mul_f32 v[6:7], v[38:39], v[6:7]
	v_pk_mul_f32 v[10:11], v[34:35], v[2:3]
	v_cvt_pk_bf16_f32 v0, v4, v5
	v_cvt_pk_bf16_f32 v1, v6, v7
	v_cvt_pk_bf16_f32 v2, v8, v9
	v_cvt_pk_bf16_f32 v3, v10, v11
	global_load_dwordx4 v[4:7], v[98:99], off offset:-128
	global_load_dwordx4 v[8:11], v[100:101], off offset:-128
	global_load_dwordx4 v[32:35], v[84:85], off offset:80
	global_load_dwordx4 v[36:39], v[84:85], off offset:64
	s_waitcnt vmcnt(3)
	v_mfma_f32_32x32x16_bf16 v[16:31], v[4:7], v[0:3], 0
	s_waitcnt vmcnt(0)
	v_mul_f32_e64 v36, v40, v36
	v_mul_f32_e64 v37, v41, v37
	v_mul_f32_e64 v38, v42, v38
	v_mul_f32_e64 v39, v43, v39
	v_pk_mul_f32 v[40:41], v[44:45], v[32:33]
	v_pk_mul_f32 v[42:43], v[46:47], v[34:35]
	v_cvt_pk_bf16_f32 v32, v36, v37
	v_cvt_pk_bf16_f32 v33, v38, v39
	v_cvt_pk_bf16_f32 v34, v40, v41
	v_cvt_pk_bf16_f32 v35, v42, v43
	global_load_dwordx4 v[36:39], v[98:99], off offset:-96
	global_load_dwordx4 v[40:43], v[100:101], off offset:-96
	v_mfma_f32_32x32x16_bf16 v[0:15], v[8:11], v[0:3], 0
	s_waitcnt vmcnt(1)
	v_mfma_f32_32x32x16_bf16 v[16:31], v[36:39], v[32:35], v[16:31]
	s_waitcnt vmcnt(0)
	v_mfma_f32_32x32x16_bf16 v[0:15], v[40:43], v[32:35], v[0:15]
	global_load_dwordx4 v[32:35], v[84:85], off offset:144
	global_load_dwordx4 v[36:39], v[84:85], off offset:128
	s_waitcnt vmcnt(1)
	v_mul_f32_e64 v40, v48, v32
	v_mul_f32_e64 v41, v49, v33
	s_waitcnt vmcnt(0)
	v_pk_mul_f32 v[36:37], v[52:53], v[36:37]
	v_pk_mul_f32 v[38:39], v[54:55], v[38:39]
	v_pk_mul_f32 v[42:43], v[50:51], v[34:35]
	v_cvt_pk_bf16_f32 v32, v36, v37
	v_cvt_pk_bf16_f32 v33, v38, v39
	v_cvt_pk_bf16_f32 v34, v40, v41
	v_cvt_pk_bf16_f32 v35, v42, v43
	global_load_dwordx4 v[36:39], v[98:99], off offset:-64
	global_load_dwordx4 v[40:43], v[100:101], off offset:-64
	s_waitcnt vmcnt(1)
	v_mfma_f32_32x32x16_bf16 v[16:31], v[36:39], v[32:35], v[16:31]
	s_waitcnt vmcnt(0)
	v_mfma_f32_32x32x16_bf16 v[0:15], v[40:43], v[32:35], v[0:15]
	global_load_dwordx4 v[32:35], v[84:85], off offset:208
	global_load_dwordx4 v[36:39], v[84:85], off offset:192
	s_waitcnt vmcnt(1)
	v_mul_f32_e64 v40, v60, v32
	v_mul_f32_e64 v41, v61, v33
	s_waitcnt vmcnt(0)
	v_pk_mul_f32 v[36:37], v[56:57], v[36:37]
	v_pk_mul_f32 v[38:39], v[58:59], v[38:39]
	v_pk_mul_f32 v[42:43], v[62:63], v[34:35]
	v_cvt_pk_bf16_f32 v32, v36, v37
	v_cvt_pk_bf16_f32 v33, v38, v39
	v_cvt_pk_bf16_f32 v34, v40, v41
	v_cvt_pk_bf16_f32 v35, v42, v43
	global_load_dwordx4 v[36:39], v[98:99], off offset:-32
	global_load_dwordx4 v[40:43], v[100:101], off offset:-32
	s_waitcnt vmcnt(1)
	v_mfma_f32_32x32x16_bf16 v[16:31], v[36:39], v[32:35], v[16:31]
	s_waitcnt vmcnt(0)
	v_mfma_f32_32x32x16_bf16 v[0:15], v[40:43], v[32:35], v[0:15]
	global_load_dwordx4 v[32:35], v[84:85], off offset:272
	global_load_dwordx4 v[36:39], v[84:85], off offset:256
	ds_read_b128 v[40:43], v105 offset:256
	ds_read_b128 v[44:47], v105 offset:272
	s_waitcnt vmcnt(0) lgkmcnt(1)
	v_pk_mul_f32 v[36:37], v[36:37], v[40:41]
	v_pk_mul_f32 v[38:39], v[38:39], v[42:43]
	s_waitcnt lgkmcnt(0)
	v_pk_mul_f32 v[40:41], v[32:33], v[44:45]
	v_pk_mul_f32 v[42:43], v[34:35], v[46:47]
	v_cvt_pk_bf16_f32 v32, v36, v37
	v_cvt_pk_bf16_f32 v33, v38, v39
	v_cvt_pk_bf16_f32 v34, v40, v41
	v_cvt_pk_bf16_f32 v35, v42, v43
	global_load_dwordx4 v[36:39], v[98:99], off
	global_load_dwordx4 v[40:43], v[100:101], off
	s_waitcnt vmcnt(1)
	v_mfma_f32_32x32x16_bf16 v[16:31], v[36:39], v[32:35], v[16:31]
	s_waitcnt vmcnt(0)
	v_mfma_f32_32x32x16_bf16 v[0:15], v[40:43], v[32:35], v[0:15]
	global_load_dwordx4 v[32:35], v[84:85], off offset:336
	global_load_dwordx4 v[36:39], v[84:85], off offset:320
	ds_read_b128 v[40:43], v105 offset:320
	s_waitcnt vmcnt(0) lgkmcnt(0)
	v_mul_f32_e64 v40, v36, v40
	v_mul_f32_e64 v41, v37, v41
	v_pk_mul_f32 v[42:43], v[38:39], v[42:43]
	ds_read_b128 v[36:39], v105 offset:336
	s_waitcnt lgkmcnt(0)
	v_pk_mul_f32 v[36:37], v[32:33], v[36:37]
	v_pk_mul_f32 v[38:39], v[34:35], v[38:39]
	v_cvt_pk_bf16_f32 v32, v40, v41
	v_cvt_pk_bf16_f32 v33, v42, v43
	v_cvt_pk_bf16_f32 v34, v36, v37
	v_cvt_pk_bf16_f32 v35, v38, v39
	global_load_dwordx4 v[36:39], v[98:99], off offset:32
	global_load_dwordx4 v[40:43], v[100:101], off offset:32
	s_waitcnt vmcnt(1)
	v_mfma_f32_32x32x16_bf16 v[16:31], v[36:39], v[32:35], v[16:31]
	s_waitcnt vmcnt(0)
	v_mfma_f32_32x32x16_bf16 v[0:15], v[40:43], v[32:35], v[0:15]
	global_load_dwordx4 v[32:35], v[84:85], off offset:400
	global_load_dwordx4 v[36:39], v[84:85], off offset:384
	s_and_saveexec_b64 s[58:59], s[0:1]
	s_cbranch_execz .LBB0_849
	ds_read_b32 v40, v105 offset:384
	s_waitcnt vmcnt(0) lgkmcnt(0)
	v_mul_f32_e32 v65, v36, v40

.LBB0_1447:
	s_barrier
	v_mov_b32_e32 v33, v244
	ds_bpermute_b32 v32, v131, v95
	v_mov_b32_e32 v133, v169
	s_add_i32 s88, s88, s67
	s_add_i32 s89, s89, s67
	s_cmpk_lt_i32 s88, 0x400
	s_waitcnt lgkmcnt(0)
	v_add_f32_e32 v32, v95, v32
	v_div_scale_f32 v34, s[0:1], v32, v32, v33
	v_rcp_f32_e32 v35, v34
	v_readlane_b32 s0, v254, 21
	v_readlane_b32 s1, v254, 22
	v_fma_f32 v36, -v34, v35, 1.0
	v_fmac_f32_e32 v35, v36, v35
	v_div_scale_f32 v36, vcc, v33, v32, v33
	v_mul_f32_e32 v37, v36, v35
	v_fma_f32 v38, -v34, v37, v36
	v_fmac_f32_e32 v37, v38, v35
	v_fma_f32 v34, -v34, v37, v36
	v_div_fmas_f32 v34, v34, v35, v37
	v_div_fixup_f32 v64, v34, v32, v33
	global_load_dwordx4 v[32:35], v[112:113], off offset:48
	global_load_dwordx4 v[36:39], v[112:113], off offset:32
	global_load_dwordx4 v[40:43], v[112:113], off offset:16
	global_load_dwordx4 v[44:47], v[112:113], off
	global_load_dwordx4 v[48:51], v[112:113], off offset:112
	global_load_dwordx4 v[52:55], v[112:113], off offset:96
	global_load_dwordx4 v[56:59], v[112:113], off offset:80
	global_load_dwordx4 v[60:63], v[112:113], off offset:64
	s_waitcnt vmcnt(7)
	v_pk_fma_f32 v[12:13], v[12:13], v[64:65], v[32:33] op_sel_hi:[1,0,1]
	v_pk_fma_f32 v[14:15], v[14:15], v[64:65], v[34:35] op_sel_hi:[1,0,1]
	v_lshl_add_u64 v[32:33], s[0:1], 0, v[134:135]
	v_lshlrev_b32_e32 v34, 7, v97
	v_mov_b32_e32 v35, v169
	s_waitcnt vmcnt(4)
	v_pk_fma_f32 v[0:1], v[0:1], v[64:65], v[44:45] op_sel_hi:[1,0,1]
	v_pk_fma_f32 v[2:3], v[2:3], v[64:65], v[46:47] op_sel_hi:[1,0,1]
	v_lshl_add_u64 v[32:33], v[32:33], 0, v[34:35]
	s_waitcnt vmcnt(0)
	v_pk_fma_f32 v[16:17], v[16:17], v[64:65], v[60:61] op_sel_hi:[1,0,1]
	v_pk_fma_f32 v[18:19], v[18:19], v[64:65], v[62:63] op_sel_hi:[1,0,1]
	v_lshl_add_u64 v[32:33], v[32:33], 0, v[132:133]
	v_cvt_pk_bf16_f32 v0, v0, v1
	v_cvt_pk_bf16_f32 v1, v2, v3
	v_pk_fma_f32 v[4:5], v[4:5], v[64:65], v[40:41] op_sel_hi:[1,0,1]
	v_pk_fma_f32 v[6:7], v[6:7], v[64:65], v[42:43] op_sel_hi:[1,0,1]
	global_store_dwordx2 v[32:33], v[0:1], off
	v_cvt_pk_bf16_f32 v0, v16, v17
	v_cvt_pk_bf16_f32 v1, v18, v19
	v_pk_fma_f32 v[20:21], v[20:21], v[64:65], v[56:57] op_sel_hi:[1,0,1]
	v_pk_fma_f32 v[22:23], v[22:23], v[64:65], v[58:59] op_sel_hi:[1,0,1]
	global_store_dwordx2 v[32:33], v[0:1], off offset:64
	v_cvt_pk_bf16_f32 v0, v4, v5
	v_cvt_pk_bf16_f32 v1, v6, v7
	v_pk_fma_f32 v[8:9], v[8:9], v[64:65], v[36:37] op_sel_hi:[1,0,1]
	v_pk_fma_f32 v[10:11], v[10:11], v[64:65], v[38:39] op_sel_hi:[1,0,1]
	global_store_dwordx2 v[32:33], v[0:1], off offset:16
	v_cvt_pk_bf16_f32 v0, v20, v21
	v_cvt_pk_bf16_f32 v1, v22, v23
	v_pk_fma_f32 v[24:25], v[24:25], v[64:65], v[52:53] op_sel_hi:[1,0,1]
	v_pk_fma_f32 v[26:27], v[26:27], v[64:65], v[54:55] op_sel_hi:[1,0,1]
	global_store_dwordx2 v[32:33], v[0:1], off offset:80
	v_cvt_pk_bf16_f32 v0, v8, v9
	v_cvt_pk_bf16_f32 v1, v10, v11
	global_store_dwordx2 v[32:33], v[0:1], off offset:32
	v_cvt_pk_bf16_f32 v0, v24, v25
	v_cvt_pk_bf16_f32 v1, v26, v27
	v_pk_fma_f32 v[28:29], v[28:29], v[64:65], v[48:49] op_sel_hi:[1,0,1]
	v_pk_fma_f32 v[30:31], v[30:31], v[64:65], v[50:51] op_sel_hi:[1,0,1]
	global_store_dwordx2 v[32:33], v[0:1], off offset:96
	v_cvt_pk_bf16_f32 v0, v12, v13
	v_cvt_pk_bf16_f32 v1, v14, v15
	global_store_dwordx2 v[32:33], v[0:1], off offset:48
	v_cvt_pk_bf16_f32 v0, v28, v29
	v_cvt_pk_bf16_f32 v1, v30, v31
	global_store_dwordx2 v[32:33], v[0:1], off offset:112
	s_cbranch_scc0 .LBB0_1566

.LBB0_1454:
	v_lshl_add_u32 v0, s80, 6, v149
	s_lshl_b32 s0, s88, 12
	s_and_b32 s76, s0, 0x6000
	v_ashrrev_i32_e32 v1, 31, v0
	v_lshl_add_u64 v[136:137], v[0:1], 0, s[76:77]
	v_readlane_b32 s0, v254, 17
	s_and_b32 s16, s88, 1
	v_lshlrev_b64 v[134:135], 10, v[136:137]
	v_readlane_b32 s1, v254, 18
	s_lshl_b32 s76, s16, 9
	v_mov_b32_e32 v131, v169
	v_lshl_add_u64 v[2:3], s[0:1], 0, v[134:135]
	v_lshl_add_u64 v[2:3], v[2:3], 0, s[76:77]
	v_lshl_add_u64 v[2:3], v[2:3], 0, v[130:131]
	v_lshlrev_b32_e32 v4, 1, v114
	v_mov_b32_e32 v5, v169
	v_lshl_add_u64 v[6:7], v[2:3], 0, v[4:5]
	global_load_dwordx4 v[2:5], v[6:7], off
	global_load_dwordx4 v[246:249], v[6:7], off offset:32
	global_load_dwordx4 v[250:253], v[6:7], off offset:64
	global_load_dwordx4 v[8:11], v[6:7], off offset:96
	v_readlane_b32 s0, v254, 23
	s_and_b32 s36, s88, 7
	v_mov_b32_e32 v1, v207
	v_add_u32_e32 v133, s0, v150
	s_mov_b64 s[0:1], 0
	s_waitcnt vmcnt(3)
	ds_write_b128 v133, v[2:5]
	s_waitcnt vmcnt(2)
	ds_write_b128 v133, v[246:249] offset:1024
	s_waitcnt vmcnt(1)
	ds_write_b128 v133, v[250:253] offset:2048
	s_waitcnt vmcnt(0)
	ds_write_b128 v133, v[8:11] offset:3072
	v_mov_b32_e32 v2, v205

.LBB0_1494:
	s_waitcnt vmcnt(3)
	v_lshl_or_b32 v97, s16, 2, v148
	v_readlane_b32 s0, v254, 19
	v_mul_u32_u24_e32 v34, 3, v97
	v_lshlrev_b64 v[32:33], 7, v[136:137]
	v_readlane_b32 s1, v254, 20
	v_lshlrev_b32_e32 v34, 2, v34
	v_mov_b32_e32 v35, v169
	v_lshl_add_u64 v[32:33], s[0:1], 0, v[32:33]
	v_lshl_add_u64 v[92:93], v[32:33], 0, v[34:35]
	global_load_dword v242, v[92:93], off
	global_load_dword v243, v[92:93], off offset:4
	global_load_dword v244, v[92:93], off offset:8
	s_mov_b64 s[0:1], -1
	s_cmp_lt_i32 s80, 16
	s_waitcnt vmcnt(0)
	v_pk_mul_f32 v[16:17], v[16:17], v[242:243] op_sel_hi:[1,0]
	v_pk_mul_f32 v[18:19], v[18:19], v[242:243] op_sel_hi:[1,0]
	v_pk_mul_f32 v[0:1], v[0:1], v[242:243] op_sel_hi:[1,0]
	v_pk_mul_f32 v[2:3], v[2:3], v[242:243] op_sel_hi:[1,0]
	global_store_dwordx4 v[112:113], v[16:19], off
	global_store_dwordx4 v[112:113], v[0:3], off offset:64
	s_nop 1
	v_pk_mul_f32 v[0:1], v[20:21], v[242:243] op_sel_hi:[1,0]
	v_pk_mul_f32 v[2:3], v[22:23], v[242:243] op_sel_hi:[1,0]
	global_store_dwordx4 v[112:113], v[0:3], off offset:16
	s_nop 1
	v_pk_mul_f32 v[0:1], v[4:5], v[242:243] op_sel_hi:[1,0]
	v_pk_mul_f32 v[2:3], v[6:7], v[242:243] op_sel_hi:[1,0]
	global_store_dwordx4 v[112:113], v[0:3], off offset:80
	s_nop 1
	v_pk_mul_f32 v[0:1], v[24:25], v[242:243] op_sel_hi:[1,0]
	v_pk_mul_f32 v[2:3], v[26:27], v[242:243] op_sel_hi:[1,0]
	global_store_dwordx4 v[112:113], v[0:3], off offset:32
	s_nop 1
	v_pk_mul_f32 v[0:1], v[8:9], v[242:243] op_sel_hi:[1,0]
	v_pk_mul_f32 v[2:3], v[10:11], v[242:243] op_sel_hi:[1,0]
	global_store_dwordx4 v[112:113], v[0:3], off offset:96
	s_nop 1
	v_pk_mul_f32 v[0:1], v[28:29], v[242:243] op_sel_hi:[1,0]
	v_pk_mul_f32 v[2:3], v[30:31], v[242:243] op_sel_hi:[1,0]
	global_store_dwordx4 v[112:113], v[0:3], off offset:48
	s_nop 1
	v_pk_mul_f32 v[0:1], v[12:13], v[242:243] op_sel_hi:[1,0]
	v_pk_mul_f32 v[2:3], v[14:15], v[242:243] op_sel_hi:[1,0]
	global_store_dwordx4 v[112:113], v[0:3], off offset:112
	s_cbranch_scc0 .LBB0_1498
	s_mov_b64 s[0:1], exec
	v_readlane_b32 s2, v254, 33
	v_readlane_b32 s3, v254, 34
	s_and_b64 s[2:3], s[0:1], s[2:3]
	s_mov_b64 exec, s[2:3]
	s_cbranch_execz .LBB0_1497
	s_add_i32 s2, s80, 1
	s_lshl_b64 s[2:3], -1, s2
	s_not_b64 s[2:3], s[2:3]
	v_mov_b32_e32 v0, s2
	v_mov_b32_e32 v1, s3
	v_mov_b32_e32 v2, v169
	v_mov_b32_e32 v3, v169
	ds_write_b128 v209, v[0:3]

.LBB0_1534:
	s_barrier
	v_mov_b32_e32 v33, v243
	ds_bpermute_b32 v32, v131, v98
	s_lshl_b32 s0, s48, 1
	s_add_u32 s5, s52, s0
	s_addc_u32 s10, s53, 0
	s_add_u32 s3, s90, s0
	s_waitcnt lgkmcnt(0)
	v_add_f32_e32 v32, v98, v32
	s_addc_u32 s4, s91, 0
	s_max_i32 s2, s80, 8
	v_div_scale_f32 v34, s[0:1], v32, v32, v33
	v_rcp_f32_e32 v35, v34
	s_add_i32 s0, s2, -8
	s_mov_b32 s1, s77
	s_lshl_b64 s[14:15], s[0:1], 13
	v_fma_f32 v36, -v34, v35, 1.0
	v_fmac_f32_e32 v35, v36, v35
	v_div_scale_f32 v36, vcc, v33, v32, v33
	v_mul_f32_e32 v37, v36, v35
	v_fma_f32 v38, -v34, v37, v36
	v_fmac_f32_e32 v37, v38, v35
	v_fma_f32 v34, -v34, v37, v36
	v_div_fmas_f32 v34, v34, v35, v37
	v_div_fixup_f32 v56, v34, v32, v33
	global_load_dwordx4 v[32:35], v[112:113], off offset:48
	global_load_dwordx4 v[36:39], v[112:113], off offset:32
	global_load_dwordx4 v[40:43], v[112:113], off offset:16
	global_load_dwordx4 v[44:47], v[112:113], off
	s_add_u32 s16, s5, s14
	s_addc_u32 s17, s10, s15
	s_add_u32 s10, s3, s14
	s_addc_u32 s11, s4, s15
	s_cmp_gt_i32 s0, s80
	s_waitcnt vmcnt(0)
	v_pk_fma_f32 v[18:19], v[18:19], v[56:57], v[46:47] op_sel_hi:[1,0,1]
	v_pk_fma_f32 v[16:17], v[16:17], v[56:57], v[44:45] op_sel_hi:[1,0,1]
	global_store_dwordx4 v[112:113], v[16:19], off
	global_load_dwordx4 v[16:19], v[112:113], off offset:112
	s_nop 0
	global_load_dwordx4 v[44:47], v[112:113], off offset:96
	global_load_dwordx4 v[48:51], v[112:113], off offset:80
	global_load_dwordx4 v[52:55], v[112:113], off offset:64
	s_waitcnt vmcnt(0)
	v_pk_fma_f32 v[2:3], v[2:3], v[56:57], v[54:55] op_sel_hi:[1,0,1]
	v_pk_fma_f32 v[0:1], v[0:1], v[56:57], v[52:53] op_sel_hi:[1,0,1]
	global_store_dwordx4 v[112:113], v[0:3], off offset:64
	s_nop 1
	v_pk_fma_f32 v[2:3], v[22:23], v[56:57], v[42:43] op_sel_hi:[1,0,1]
	v_pk_fma_f32 v[0:1], v[20:21], v[56:57], v[40:41] op_sel_hi:[1,0,1]
	global_store_dwordx4 v[112:113], v[0:3], off offset:16
	s_nop 1
	v_pk_fma_f32 v[2:3], v[6:7], v[56:57], v[50:51] op_sel_hi:[1,0,1]
	v_pk_fma_f32 v[0:1], v[4:5], v[56:57], v[48:49] op_sel_hi:[1,0,1]
	global_store_dwordx4 v[112:113], v[0:3], off offset:80
	s_nop 1
	v_pk_fma_f32 v[2:3], v[26:27], v[56:57], v[38:39] op_sel_hi:[1,0,1]
	v_pk_fma_f32 v[0:1], v[24:25], v[56:57], v[36:37] op_sel_hi:[1,0,1]
	global_store_dwordx4 v[112:113], v[0:3], off offset:32
	s_nop 1
	v_pk_fma_f32 v[2:3], v[10:11], v[56:57], v[46:47] op_sel_hi:[1,0,1]
	v_pk_fma_f32 v[0:1], v[8:9], v[56:57], v[44:45] op_sel_hi:[1,0,1]
	global_store_dwordx4 v[112:113], v[0:3], off offset:96
	s_nop 1
	v_pk_fma_f32 v[2:3], v[30:31], v[56:57], v[34:35] op_sel_hi:[1,0,1]
	v_pk_fma_f32 v[0:1], v[28:29], v[56:57], v[32:33] op_sel_hi:[1,0,1]
	global_store_dwordx4 v[112:113], v[0:3], off offset:48
	s_nop 1
	v_pk_fma_f32 v[2:3], v[14:15], v[56:57], v[18:19] op_sel_hi:[1,0,1]
	v_pk_fma_f32 v[0:1], v[12:13], v[56:57], v[16:17] op_sel_hi:[1,0,1]
	global_store_dwordx4 v[112:113], v[0:3], off offset:112
	ds_read_b128 v[66:69], v133
	ds_read_b128 v[70:73], v133 offset:1024
	ds_read_b128 v[74:77], v133 offset:2048
	ds_read_b128 v[78:81], v133 offset:3072
	v_lshl_add_u64 v[0:1], s[16:17], 0, v[168:169]
	v_lshl_add_u64 v[0:1], v[0:1], 0, s[96:97]
	global_load_dwordx4 v[82:85], v[0:1], off
	v_lshl_add_u64 v[0:1], s[10:11], 0, v[168:169]
	v_lshl_add_u64 v[0:1], v[0:1], 0, s[96:97]
	global_load_dwordx4 v[86:89], v[0:1], off
	s_waitcnt vmcnt(1)
	ds_write_b128 v151, v[82:85]
	s_waitcnt vmcnt(0)
	ds_write_b128 v152, v[86:89] offset:32768
	s_waitcnt lgkmcnt(0)
	s_barrier
	s_cbranch_scc1 .LBB0_1561
	s_lshl_b32 s0, s2, 13
	s_add_i32 s0, s0, 0xffff2000
	v_mov_b32_e32 v32, 0
	s_add_u32 s0, s76, s0
	v_mov_b32_e32 v34, v32
	v_mov_b32_e32 v35, v32
	v_mov_b32_e32 v36, v32
	v_mov_b32_e32 v37, v32
	v_mov_b32_e32 v38, v32
	v_mov_b32_e32 v39, v32
	v_mov_b32_e32 v40, v32
	v_mov_b32_e32 v41, v32
	v_mov_b32_e32 v42, v32
	v_mov_b32_e32 v43, v32
	v_mov_b32_e32 v44, v32
	v_mov_b32_e32 v45, v32
	v_mov_b32_e32 v46, v32
	v_mov_b32_e32 v47, v32
	v_mov_b32_e32 v16, v169
	v_mov_b32_e32 v17, v169
	s_addc_u32 s1, 0, 0
	v_mov_b32_e32 v33, v32
	v_mov_b32_e32 v18, v169
	v_mov_b32_e32 v19, v169
	v_mov_b32_e32 v20, v169
	v_mov_b32_e32 v21, v169
	v_mov_b32_e32 v22, v169
	v_mov_b32_e32 v23, v169
	v_mov_b32_e32 v24, v169
	v_mov_b32_e32 v25, v169
	v_mov_b32_e32 v26, v169
	v_mov_b32_e32 v27, v169
	v_mov_b32_e32 v28, v169
	v_mov_b32_e32 v29, v169
	v_mov_b32_e32 v30, v169
	v_mov_b32_e32 v31, v169
	v_mov_b64_e32 v[0:1], v[16:17]
	v_mov_b64_e32 v[48:49], v[46:47]
	s_mov_b64 s[82:83], s[52:53]
	v_lshl_add_u64 v[90:91], v[128:129], 0, s[0:1]
	s_sub_i32 s76, 0, s80
	s_add_i32 s0, s2, -9
	s_mov_b64 s[10:11], 0
	v_mov_b32_e32 v95, v32
	v_mov_b32_e32 v100, v32
	v_mov_b64_e32 v[2:3], v[18:19]
	v_mov_b64_e32 v[4:5], v[20:21]
	v_mov_b64_e32 v[6:7], v[22:23]
	v_mov_b64_e32 v[8:9], v[24:25]
	v_mov_b64_e32 v[10:11], v[26:27]
	v_mov_b64_e32 v[12:13], v[28:29]
	v_mov_b64_e32 v[14:15], v[30:31]
	v_mov_b32_e32 v96, v32
	v_mov_b32_e32 v98, v32
	v_mov_b32_e32 v99, v32
	v_mov_b64_e32 v[46:47], v[44:45]
	v_mov_b64_e32 v[44:45], v[42:43]
	v_mov_b64_e32 v[42:43], v[40:41]
	v_mov_b64_e32 v[40:41], v[38:39]
	v_mov_b64_e32 v[38:39], v[36:37]
	v_mov_b64_e32 v[36:37], v[34:35]
	v_mov_b64_e32 v[34:35], v[32:33]
